# w_in transpose split between the ADA-phase transposers and the D1 tail moved from item 8832 to 8192 (ADA transposers were the phase's stragglers)
# speedup vs baseline: 1.0043x; 1.0043x over previous
.LT_ret1:
	s_sub_u32 s65, s65, s68
	s_mov_b32 s64, 3
	s_mov_b32 s68, 0x2000
	s_mov_b32 s67, 2
	s_branch .LT_entry

.LBB0_586:
	s_cmp_lt_i32 s34, s33
	s_cbranch_scc1 .LBB0_595
	s_sub_i32 s2, s34, s33
	v_lshrrev_b32_e32 v0, 6, v128
	v_lshl_add_u32 v1, s2, 3, v0
	v_add_u32_e32 v12, 0x2000, v1
	s_movk_i32 s2, 0x2e00
	v_cmp_gt_i32_e32 vcc, s2, v12
	s_and_saveexec_b64 s[2:3], vcc
	s_cbranch_execz .LBB0_594
	s_sub_i32 s4, s94, s33
	s_waitcnt vmcnt(0)
	v_lshlrev_b32_e32 v3, 3, v128
	s_lshl_b32 s8, s4, 3
	s_movk_i32 s4, 0x2200
	v_lshlrev_b32_e32 v2, 2, v128
	v_bfe_u32 v13, v128, 3, 3
	v_and_b32_e32 v3, 56, v3
	v_readlane_b32 s52, v235, 1
	v_mad_u32_u24 v1, v0, s4, 0
	v_and_b32_e32 v6, 0x7c, v2
	v_mul_u32_u24_e32 v4, 0x84, v3
	v_lshlrev_b32_e32 v5, 2, v13
	v_mov_b32_e32 v7, 0
	v_readlane_b32 s58, v235, 7
	v_readlane_b32 s59, v235, 8
	v_add_u32_e32 v2, v1, v6
	v_add3_u32 v14, v1, v4, v5
	v_lshl_add_u64 v[4:5], s[58:59], 0, v[6:7]
	v_lshlrev_b32_e32 v6, 1, v3
	v_bfe_u32 v0, v128, 5, 1
	v_lshl_add_u64 v[6:7], s[50:51], 0, v[6:7]
	s_mov_b64 s[4:5], 0x4204000
	s_movk_i32 s9, 0x84
	v_or_b32_e32 v15, 8, v13
	v_or_b32_e32 v16, 16, v13
	v_or_b32_e32 v17, 24, v13
	v_mov_b32_e32 v1, v0
	v_lshl_add_u64 v[6:7], v[6:7], 0, s[4:5]
	s_mov_b64 s[4:5], 0
	s_mov_b32 s10, 0xb21642c9
	s_movk_i32 s11, 0xfe90
	s_movk_i32 s12, 0xf7ff
	s_movk_i32 s13, 0xfc00
	s_mov_b32 s14, 0xb800
	s_movk_i32 s15, 0x2dff
	v_readlane_b32 s53, v235, 2
	v_readlane_b32 s54, v235, 3
	v_readlane_b32 s55, v235, 4
	v_readlane_b32 s56, v235, 5
	v_readlane_b32 s57, v235, 6
	v_readlane_b32 s60, v235, 9
	v_readlane_b32 s61, v235, 10
	v_readlane_b32 s62, v235, 11
	v_readlane_b32 s63, v235, 12
	v_readlane_b32 s64, v235, 13
	v_readlane_b32 s65, v235, 14
	v_readlane_b32 s66, v235, 15
	v_readlane_b32 s67, v235, 16

.LBB0_671:
.LBB0_672:
	v_lshrrev_b32_e32 v0, 6, v128
	v_lshl_add_u32 v1, s34, 3, v0
	v_add_u32_e32 v12, 0x2000, v1
	s_movk_i32 s2, 0x2e00
	v_cmp_gt_i32_e32 vcc, s2, v12
	s_and_saveexec_b64 s[2:3], vcc
	s_cbranch_execz .LBB0_679
	s_waitcnt vmcnt(0)
	v_lshlrev_b32_e32 v3, 3, v128
	s_movk_i32 s4, 0x2200
	v_lshlrev_b32_e32 v2, 2, v128
	v_bfe_u32 v13, v128, 3, 3
	v_and_b32_e32 v3, 56, v3
	v_readlane_b32 s52, v235, 1
	v_mad_u32_u24 v1, v0, s4, 0
	v_and_b32_e32 v6, 0x7c, v2
	v_mul_u32_u24_e32 v4, 0x84, v3
	v_lshlrev_b32_e32 v5, 2, v13
	v_mov_b32_e32 v7, 0
	v_readlane_b32 s58, v235, 7
	v_readlane_b32 s59, v235, 8
	v_add_u32_e32 v2, v1, v6
	v_add3_u32 v14, v1, v4, v5
	v_lshl_add_u64 v[4:5], s[58:59], 0, v[6:7]
	v_lshlrev_b32_e32 v6, 1, v3
	v_bfe_u32 v0, v128, 5, 1
	v_lshl_add_u64 v[6:7], s[50:51], 0, v[6:7]
	s_mov_b64 s[4:5], 0x4204000
	s_lshl_b32 s8, s94, 3
	s_movk_i32 s9, 0x84
	v_or_b32_e32 v15, 8, v13
	v_or_b32_e32 v16, 16, v13
	v_or_b32_e32 v17, 24, v13
	v_lshl_add_u64 v[6:7], v[6:7], 0, s[4:5]
	v_mov_b32_e32 v1, v0
	s_mov_b64 s[4:5], 0
	s_mov_b32 s10, 0xb21642c9
	s_movk_i32 s11, 0xfe90
	s_movk_i32 s12, 0xf7ff
	s_movk_i32 s13, 0xfc00
	s_mov_b32 s14, 0xb800
	s_movk_i32 s15, 0x2dff
	v_readlane_b32 s53, v235, 2
	v_readlane_b32 s54, v235, 3
	v_readlane_b32 s55, v235, 4
	v_readlane_b32 s56, v235, 5
	v_readlane_b32 s57, v235, 6
	v_readlane_b32 s60, v235, 9
	v_readlane_b32 s61, v235, 10
	v_readlane_b32 s62, v235, 11
	v_readlane_b32 s63, v235, 12
	v_readlane_b32 s64, v235, 13
	v_readlane_b32 s65, v235, 14
	v_readlane_b32 s66, v235, 15
	v_readlane_b32 s67, v235, 16
